# P4: LRU/diff-attention output pass split 6/10 between the GLU-GEMM workgroups and the others; attention units re-dealt 36/32 between early and late workgroups; P1 and P9 epilogue partial-sum loads bat
# baseline (speedup 1.0000x reference)
;   __device__ __forceinline__ bool next(int i,AttnUnit&u)const{
;     if(G==256){ if(i>=4)return false; const int s=vcu&3; u.bh=vcu>>2; u.qb=(i==0)?s:(i==1)?7-s:(i==2)?8+s:15-s; return true; }
;     const int L=i*G+vcu; if(L>=BATCH*NHEAD*NQB)return false; u.bh=L/NQB; u.qb=NQB-1-(L%NQB); return true; }
;   AttnUnit u;
;   for(int i=0;S.next(i,u);++i){ S.a_ready(u); attn_unit<THRL>(u.bh/NHEAD,u.bh%NHEAD,u.qb,T.Q,T.K,T.V,T.O,lds); S.done(u); }
.LBB0_549:
	s_andn2_b64 vcc, exec, s[6:7]
	s_cbranch_vccnz .LBB0_558
	s_bfe_u32 s3, s22, 0x10004
	s_and_b32 s10, s22, 3
	s_lshl_b32 s3, s3, 2
	s_or_b32 s3, s3, s10
	s_mov_b32 s10, 0x8a6a6f
	s_cmp_eq_u32 s3, 1
	s_cselect_b32 s10, 0x8e5aae, s10
	s_cmp_eq_u32 s3, 2
	s_cselect_b32 s10, 0x867aed, s10
	s_cmp_eq_u32 s3, 3
	s_cselect_b32 s10, 0x20937a2c, s10
	s_cmp_eq_u32 s3, 4
	s_cselect_b32 s10, 0x26a2f, s10
	s_cmp_eq_u32 s3, 5
	s_cselect_b32 s10, 0x825a6e, s10
	s_cmp_eq_u32 s3, 6
	s_cselect_b32 s10, 0x864aad, s10
	s_cmp_eq_u32 s3, 7
	s_cselect_b32 s10, 0x8a3aec, s10
	s_mul_i32 s3, s70, 6
	s_min_u32 s3, s3, 31
	s_lshr_b32 s10, s10, s3
	s_bitcmp1_b32 s10, 5
	s_cbranch_scc0 .Lau_done
	s_and_b32 s72, s10, 15
	s_lshr_b32 s3, s10, 2
	s_and_b32 s3, s3, 4
	s_xor_b32 s71, s60, s3
	s_mov_b64 s[4:5], -1
	s_branch .LBB0_559
.Lau_done:
	s_mov_b64 s[4:5], -1
	s_branch .LBB0_545
